# decode level-1 queue order: heads interleaved fastest (was head-major) so concurrent streams cover all HBM channels
# speedup vs baseline: 1.0250x; 1.0250x over previous
; __device__ __forceinline__ void decode_wave_loop(const int* ptab, const float* ck, const float* cv, const float* sbbias, unsigned char* ws, LAS unsigned char* wlds, unsigned* qhead, int lane) {
;     ...
;         unsigned it = 0; if (lane == 0) it = __hip_atomic_fetch_add(qhead, 1u, __ATOMIC_RELAXED, __HIP_MEMORY_SCOPE_AGENT);
;         it = __builtin_amdgcn_readfirstlane(it);
;         if (it >= (unsigned)N_DEC_ITEMS) break;
;         int seq, head, page0, npages;
;         if (it < (unsigned)N_DEC_L0) { head = it & 7; page0 = L0_FIRST + ((it >> 3) & 31); seq = it >> 8; npages = 1; }
;         else {
;             const int j = (int)it - N_DEC_L0, rem = j % (DSEQ * (L0_FIRST / 2));
;             head = 7 - j / (DSEQ * (L0_FIRST / 2)); seq = rem / (L0_FIRST / 2); page0 = 2 * (rem % (L0_FIRST / 2)); npages = 2;
;             const int key = seq * 8 + head;
;             if (key != ckey) {
;                 unsigned ok = 1u, sp = 0u;
;                 while (__builtin_amdgcn_readfirstlane(__hip_atomic_load(l0cnt + 64 * key, __ATOMIC_RELAXED, __HIP_MEMORY_SCOPE_AGENT)) < (unsigned)L0_PAGES) { __builtin_amdgcn_s_sleep(8); if (++sp > (1u << 20)) { ok = 0u; break; } }
;                 cskip = ok ? decode_skip_old_pages<true>((const float*)(ws + WS_FPART), seq, head, lane) : false; ckey = key;
;             }
;             if (cskip) continue;
.LBB0_971:
	s_or_b64 exec, exec, s[20:21]
	v_readfirstlane_b32 s31, v2
	s_cmpk_gt_u32 s31, 0x13ff
	s_mov_b64 s[20:21], -1
	s_cbranch_scc1 .LBB0_966
	s_cmpk_lt_u32 s31, 0x800
	s_cselect_b64 s[34:35], -1, 0
	s_cmpk_gt_u32 s31, 0x7ff
	s_mov_b64 s[22:23], -1
	s_mov_b64 s[28:29], 0
	s_mov_b64 s[20:21], 0
	s_cbranch_scc0 .LBB0_982
	s_add_i32 s20, s31, 0xf800
	s_and_b32 s20, s20, 0xffff
	s_and_b32 s21, s20, 7
	s_lshr_b32 s44, s20, 3
	s_and_b32 s20, s44, 0xffff
	s_mul_i32 s20, s20, 0xaaab
	s_lshr_b32 s71, s20, 21
	s_sub_i32 s30, 7, s21
	s_lshl_b32 s75, s71, 3
	s_or_b32 s48, s75, s30
	s_cmp_eq_u32 s48, s52
	s_mov_b32 s46, s52
	s_mov_b64 s[20:21], s[16:17]
	s_cbranch_scc1 .LBB0_981
	s_lshl_b32 s20, s48, 8
	s_add_u32 s20, s24, s20
	s_addc_u32 s21, s33, 0
	s_mov_b32 s49, 0x100001
	s_branch .LBB0_976
